# diff-attn main loop rewritten: QK1 hoisted beside QK0, persistent C-init tuple, softmax VALU interleaved between PV MFMAs, in-place exp, sums as plain-add tree
# speedup vs baseline: 1.0254x; 1.0254x over previous
.LBB0_266:
	v_mad_i64_i32 v[152:153], s[18:19], v171, s93, 0
	s_ashr_i32 s15, s14, 31
	s_lshr_b32 s18, s65, 6
	v_exp_f32_e32 v130, v64
	v_exp_f32_e32 v131, v65
	v_exp_f32_e32 v132, v66
	v_exp_f32_e32 v133, v67
	v_exp_f32_e32 v134, v68
	v_exp_f32_e32 v135, v69
	v_exp_f32_e32 v136, v70
	v_exp_f32_e32 v137, v71
	v_exp_f32_e32 v138, v72
	v_exp_f32_e32 v139, v73
	v_exp_f32_e32 v140, v74
	v_exp_f32_e32 v141, v75
	v_exp_f32_e32 v142, v76
	v_exp_f32_e32 v143, v77
	v_exp_f32_e32 v144, v78
	v_exp_f32_e32 v145, v79
	s_nop 0
	v_cvt_pk_bf16_f32 v67, v144, v145
	v_cvt_pk_bf16_f32 v71, v136, v137
	v_cvt_pk_bf16_f32 v66, v142, v143
	v_cvt_pk_bf16_f32 v70, v134, v135
	v_cvt_pk_bf16_f32 v65, v140, v141
	v_cvt_pk_bf16_f32 v69, v132, v133
	v_cvt_pk_bf16_f32 v64, v138, v139
	v_cvt_pk_bf16_f32 v68, v130, v131
	s_setprio 1
	s_waitcnt lgkmcnt(3)
	v_mfma_f32_32x32x16_bf16 v[0:15], v[68:71], v[126:129], v[0:15]
	s_waitcnt lgkmcnt(2)
	v_mfma_f32_32x32x16_bf16 v[16:31], v[68:71], v[114:117], v[16:31]
	s_waitcnt lgkmcnt(1)
	v_mfma_f32_32x32x16_bf16 v[0:15], v[64:67], v[122:125], v[0:15]
	s_waitcnt lgkmcnt(0)
	v_mfma_f32_32x32x16_bf16 v[16:31], v[64:67], v[118:121], v[16:31]
	s_setprio 0
	ds_read_b128 v[72:75], v195 offset:57344
	ds_read_b128 v[76:79], v195 offset:61440
	ds_read_b128 v[114:117], v196 offset:57344
	ds_read_b128 v[118:121], v196 offset:61440
	s_setprio 1
	s_waitcnt lgkmcnt(3)
	v_mfma_f32_32x32x16_bf16 v[32:47], v[68:71], v[72:75], v[32:47]
	s_waitcnt lgkmcnt(2)
	v_mfma_f32_32x32x16_bf16 v[48:63], v[68:71], v[76:79], v[48:63]
	s_waitcnt lgkmcnt(1)
	v_mfma_f32_32x32x16_bf16 v[32:47], v[64:67], v[114:117], v[32:47]
	s_waitcnt lgkmcnt(0)
	v_mfma_f32_32x32x16_bf16 v[48:63], v[64:67], v[118:121], v[48:63]
	s_setprio 0
	v_add_f32_e64 v64, v132, v130
	v_add_f32_e64 v65, v133, v131
	v_lshlrev_b32_e32 v68, 1, v170
	v_add_f32_e64 v64, v134, v64
	v_add_f32_e64 v65, v135, v65
	v_add_u32_e32 v66, 0x80, v68
	v_pk_add_f32 v[64:65], v[136:137], v[64:65]
	s_add_i32 s19, s69, 0xffffff41
	v_pk_add_f32 v[64:65], v[138:139], v[64:65]
	s_mov_b32 s64, 4
	v_pk_add_f32 v[64:65], v[140:141], v[64:65]
	s_nop 0
	v_pk_add_f32 v[64:65], v[142:143], v[64:65]
	s_nop 0
	v_pk_add_f32 v[64:65], v[144:145], v[64:65]
	s_nop 0
	v_add_f32_e32 v64, v64, v65
	v_add_f32_e32 v174, v80, v64
	v_lshl_add_u64 v[64:65], v[152:153], 0, s[16:17]
	v_lshl_add_u64 v[64:65], v[150:151], 1, v[64:65]
	v_lshl_add_u64 v[150:151], s[12:13], 0, v[64:65]
	v_mov_b64_e32 v[64:65], s[4:5]
	v_mad_i64_i32 v[66:67], s[4:5], v66, s65, v[64:65]
	v_mad_i64_i32 v[64:65], s[4:5], v68, s65, v[64:65]
	v_lshl_add_u64 v[64:65], v[64:65], 0, v[184:185]
	v_lshl_add_u64 v[154:155], s[8:9], 0, v[64:65]
	v_add_lshl_u32 v64, s69, v172, 2
	s_mul_i32 s16, s62, s65
	v_lshl_add_u64 v[66:67], v[66:67], 0, v[184:185]
	v_sub_u32_e32 v64, v156, v64
	s_lshl_b32 s72, s16, 1
	v_lshl_add_u64 v[152:153], s[8:9], 0, v[66:67]
	v_add_u32_e32 v148, s63, v64
	s_sub_i32 s65, s90, s68
	s_movk_i32 s68, 0xc0
	v_mov_b32_e32 v220, 0
	v_mov_b32_e32 v221, 0
	v_mov_b32_e32 v222, 0
	v_mov_b32_e32 v223, 0
	v_mov_b32_e32 v224, 0
	v_mov_b32_e32 v225, 0
	v_mov_b32_e32 v226, 0
	v_mov_b32_e32 v227, 0
	v_mov_b32_e32 v228, 0
	v_mov_b32_e32 v229, 0
	v_mov_b32_e32 v230, 0
	v_mov_b32_e32 v231, 0
	v_mov_b32_e32 v232, 0
	v_mov_b32_e32 v233, 0
	v_mov_b32_e32 v234, 0
	v_mov_b32_e32 v235, 0
	v_mov_b32_e32 v184, v174
	s_branch .LBB0_268
.LBB0_268:
	v_lshl_add_u64 v[158:159], v[154:155], 0, s[72:73]
	v_lshl_add_u64 v[156:157], v[152:153], 0, s[72:73]
	s_waitcnt vmcnt(3)
	ds_write_b128 v180, v[98:101]
	s_waitcnt vmcnt(2)
	ds_write_b128 v180, v[102:105] offset:8192
	s_waitcnt vmcnt(0)
	ds_write2st64_b64 v178, v[106:107], v[110:111] offset0:32 offset1:48
	ds_write2st64_b64 v179, v[108:109], v[112:113] offset0:32 offset1:48
	s_waitcnt lgkmcnt(0)
	s_barrier
	ds_read_b128 v[114:117], v181
	ds_read_b128 v[118:121], v182
	ds_read_b128 v[122:125], v183
	ds_read_b128 v[126:129], v192
	ds_read_b128 v[142:145], v181 offset:8192
	ds_read_b128 v[138:141], v182 offset:8192
	ds_read_b128 v[134:137], v183 offset:8192
	ds_read_b128 v[130:133], v192 offset:8192
	s_add_i32 s4, s64, -1
	s_cmp_ge_u32 s4, s18
	s_cbranch_scc1 .Ldf_nold0
	v_add_co_u32_e32 v64, vcc, 0xfff94000, v150
	s_nop 1
	v_addc_co_u32_e32 v65, vcc, -1, v151, vcc
	v_add_co_u32_e32 v66, vcc, 0xfffb8000, v150
	s_nop 1
	v_addc_co_u32_e32 v67, vcc, -1, v151, vcc
	global_load_dwordx4 v[98:101], v[64:65], off
	global_load_dwordx4 v[102:105], v[66:67], off
	v_add_co_u32_e32 v64, vcc, 0x2f800000, v158
	s_nop 1
	v_addc_co_u32_e32 v65, vcc, 0, v159, vcc
	global_load_dwordx4 v[106:109], v[64:65], off offset:384
	v_add_co_u32_e32 v64, vcc, 0x2f800000, v156
	s_nop 1
	v_addc_co_u32_e32 v65, vcc, 0, v157, vcc
	global_load_dwordx4 v[110:113], v[64:65], off offset:384
.Ldf_nold0:
	s_sub_i32 s4, s68, 64
	s_cmp_le_i32 s4, s19
	s_cselect_b64 s[16:17], -1, 0
	s_cmp_gt_i32 s4, s19
	s_cselect_b64 vcc, -1, 0
	s_add_i32 s69, s65, s68
	s_add_i32 s4, s69, 0xffffffa1
	s_cmpk_gt_i32 s4, 0x7f
	s_cselect_b64 s[54:55], -1, 0
	s_and_b64 s[4:5], vcc, s[54:55]
	v_cndmask_b32_e64 v64, 0, v147, s[4:5]
	v_cndmask_b32_e32 v253, v146, v64, vcc
	s_or_b64 s[4:5], s[16:17], s[54:55]
	v_sub_f32_e32 v64, v253, v149
	v_cmp_ne_u32_e32 vcc, v64, v220
	s_cbranch_vccz .Ldf_ci0
	v_mov_b32_e32 v220, v64
	v_mov_b32_e32 v221, v64
	v_mov_b32_e32 v222, v64
	v_mov_b32_e32 v223, v64
	v_mov_b32_e32 v224, v64
	v_mov_b32_e32 v225, v64
	v_mov_b32_e32 v226, v64
	v_mov_b32_e32 v227, v64
	v_mov_b32_e32 v228, v64
	v_mov_b32_e32 v229, v64
	v_mov_b32_e32 v230, v64
	v_mov_b32_e32 v231, v64
	v_mov_b32_e32 v232, v64
	v_mov_b32_e32 v233, v64
	v_mov_b32_e32 v234, v64
	v_mov_b32_e32 v235, v64
.Ldf_ci0:
	s_nop 0
	s_waitcnt lgkmcnt(7)
	v_mfma_f32_32x32x16_bf16 v[66:81], v[114:117], v[82:85], v[220:235]
	s_waitcnt lgkmcnt(6)
	v_mfma_f32_32x32x16_bf16 v[66:81], v[118:121], v[86:89], v[66:81]
	s_waitcnt lgkmcnt(5)
	v_mfma_f32_32x32x16_bf16 v[66:81], v[122:125], v[90:93], v[66:81]
	s_waitcnt lgkmcnt(4)
	v_mfma_f32_32x32x16_bf16 v[66:81], v[126:129], v[94:97], v[66:81]
	s_waitcnt lgkmcnt(3)
	v_mfma_f32_32x32x16_bf16 v[236:251], v[142:145], v[82:85], v[220:235]
	ds_read_b128 v[126:129], v193 offset:16384
	ds_read_b128 v[114:117], v193 offset:20480
	s_waitcnt lgkmcnt(4)
	v_mfma_f32_32x32x16_bf16 v[236:251], v[138:141], v[86:89], v[236:251]
	ds_read_b128 v[122:125], v194 offset:16384
	ds_read_b128 v[118:121], v194 offset:20480
	s_waitcnt lgkmcnt(5)
	v_mfma_f32_32x32x16_bf16 v[236:251], v[134:137], v[90:93], v[236:251]
	s_waitcnt lgkmcnt(4)
	v_mfma_f32_32x32x16_bf16 v[236:251], v[130:133], v[94:97], v[236:251]
	ds_read_b128 v[130:133], v193 offset:24576
	ds_read_b128 v[134:137], v193 offset:28672
	ds_read_b128 v[138:141], v194 offset:24576
	ds_read_b128 v[142:145], v194 offset:28672
	s_and_b64 vcc, exec, s[4:5]
	s_cbranch_vccnz .Ldf_nb0_0
	ds_read2_b32 v[160:161], v148 offset1:1
	ds_read2_b32 v[162:163], v148 offset0:2 offset1:3
	ds_read2_b32 v[164:165], v148 offset0:8 offset1:9
	ds_read2_b32 v[166:167], v148 offset0:10 offset1:11
	ds_read2_b32 v[168:169], v148 offset0:16 offset1:17
	ds_read2_b32 v[170:171], v148 offset0:18 offset1:19
	ds_read2_b32 v[172:173], v148 offset0:24 offset1:25
	ds_read2_b32 v[174:175], v148 offset0:26 offset1:27
	s_waitcnt lgkmcnt(7)
	v_pk_add_f32 v[66:67], v[66:67], v[160:161]
	s_waitcnt lgkmcnt(6)
	v_pk_add_f32 v[68:69], v[68:69], v[162:163]
	s_waitcnt lgkmcnt(5)
	v_pk_add_f32 v[70:71], v[70:71], v[164:165]
	s_waitcnt lgkmcnt(4)
	v_pk_add_f32 v[72:73], v[72:73], v[166:167]
	s_waitcnt lgkmcnt(3)
	v_pk_add_f32 v[74:75], v[74:75], v[168:169]
	s_waitcnt lgkmcnt(2)
	v_pk_add_f32 v[76:77], v[76:77], v[170:171]
	s_waitcnt lgkmcnt(1)
	v_pk_add_f32 v[78:79], v[78:79], v[172:173]
	s_waitcnt lgkmcnt(0)
	v_pk_add_f32 v[80:81], v[80:81], v[174:175]
	s_nop 0
.Ldf_nb0_0:
	v_max_f32_e32 v64, v67, v67
	v_max_f32_e32 v65, v66, v66
	v_max_f32_e32 v64, v65, v64
	v_max3_f32 v64, v64, v68, v69
	v_max3_f32 v64, v64, v70, v71
	v_max3_f32 v64, v64, v72, v73
	v_max3_f32 v64, v64, v74, v75
	v_max3_f32 v64, v64, v76, v77
	v_max3_f32 v64, v64, v78, v79
	v_max3_f32 v64, v64, v80, v81
	v_mov_b32_e32 v65, v64
	s_nop 1
	v_permlane32_swap_b32_e32 v64, v65
	v_max_f32_e32 v65, v65, v65
	v_max_f32_e32 v64, v64, v64
	v_max_f32_e32 v64, v64, v65
	v_cmp_lt_f32_e32 vcc, s97, v64
	s_cbranch_vccnz .Ldf_rare0_0
.Ldf_back0_0:
	v_exp_f32_e32 v66, v66
	v_exp_f32_e32 v67, v67
	v_exp_f32_e32 v68, v68
	v_exp_f32_e32 v69, v69
	v_exp_f32_e32 v70, v70
	v_exp_f32_e32 v71, v71
	v_exp_f32_e32 v72, v72
	v_exp_f32_e32 v73, v73
	v_exp_f32_e32 v74, v74
	v_exp_f32_e32 v75, v75
	v_exp_f32_e32 v76, v76
	v_exp_f32_e32 v77, v77
	v_exp_f32_e32 v78, v78
	v_exp_f32_e32 v79, v79
	v_exp_f32_e32 v80, v80
	v_exp_f32_e32 v81, v81
	v_cvt_pk_bf16_f32 v200, v66, v67
	v_cvt_pk_bf16_f32 v201, v68, v69
	v_cvt_pk_bf16_f32 v202, v70, v71
	v_cvt_pk_bf16_f32 v203, v72, v73
	v_cvt_pk_bf16_f32 v204, v74, v75
	v_cvt_pk_bf16_f32 v205, v76, v77
	v_cvt_pk_bf16_f32 v206, v78, v79
	v_cvt_pk_bf16_f32 v207, v80, v81
	s_waitcnt lgkmcnt(7)
	v_mfma_f32_32x32x16_bf16 v[0:15], v[200:203], v[126:129], v[0:15]
	v_add_f32_e32 v168, v66, v67
	v_add_f32_e32 v169, v68, v69
	v_add_f32_e32 v170, v70, v71
	v_add_f32_e32 v171, v72, v73
	v_add_f32_e32 v172, v74, v75
	v_add_f32_e32 v173, v76, v77
	s_waitcnt lgkmcnt(6)
	v_mfma_f32_32x32x16_bf16 v[16:31], v[200:203], v[114:117], v[16:31]
	v_add_f32_e32 v174, v78, v79
	v_add_f32_e32 v175, v80, v81
	v_add_f32_e32 v168, v168, v169
	v_add_f32_e32 v170, v170, v171
	v_add_f32_e32 v172, v172, v173
	s_waitcnt lgkmcnt(5)
	v_mfma_f32_32x32x16_bf16 v[0:15], v[204:207], v[122:125], v[0:15]
	v_add_f32_e32 v174, v174, v175
	v_add_f32_e32 v168, v168, v170
	v_add_f32_e32 v172, v172, v174
	v_add_f32_e32 v168, v168, v172
	v_add_f32_e32 v184, v184, v168
	s_waitcnt lgkmcnt(4)
	v_mfma_f32_32x32x16_bf16 v[16:31], v[204:207], v[118:121], v[16:31]
	s_xor_b64 s[4:5], s[4:5], -1
	s_andn2_b64 vcc, exec, s[4:5]
	s_cbranch_vccnz .Ldf_nb1_0
	ds_read2_b32 v[160:161], v148 offset0:32 offset1:33
	ds_read2_b32 v[162:163], v148 offset0:34 offset1:35
	ds_read2_b32 v[164:165], v148 offset0:40 offset1:41
	ds_read2_b32 v[166:167], v148 offset0:42 offset1:43
	ds_read2_b32 v[168:169], v148 offset0:48 offset1:49
	ds_read2_b32 v[170:171], v148 offset0:50 offset1:51
	ds_read2_b32 v[172:173], v148 offset0:56 offset1:57
	ds_read2_b32 v[174:175], v148 offset0:58 offset1:59
	s_waitcnt lgkmcnt(7)
	v_pk_add_f32 v[236:237], v[236:237], v[160:161]
	s_waitcnt lgkmcnt(6)
	v_pk_add_f32 v[238:239], v[238:239], v[162:163]
	s_waitcnt lgkmcnt(5)
	v_pk_add_f32 v[240:241], v[240:241], v[164:165]
	s_waitcnt lgkmcnt(4)
	v_pk_add_f32 v[242:243], v[242:243], v[166:167]
	s_waitcnt lgkmcnt(3)
	v_pk_add_f32 v[244:245], v[244:245], v[168:169]
	s_waitcnt lgkmcnt(2)
	v_pk_add_f32 v[246:247], v[246:247], v[170:171]
	s_waitcnt lgkmcnt(1)
	v_pk_add_f32 v[248:249], v[248:249], v[172:173]
	s_waitcnt lgkmcnt(0)
	v_pk_add_f32 v[250:251], v[250:251], v[174:175]
	s_nop 0
; template <int KW, int DV, bool BIAS> ...
;     ...
;     for (int t = 0; t < NT; t += 2) { TILE(0, t); TILE(1, t + 1); }
.Ldf_nb1_0:
	v_max_f32_e32 v64, v237, v237
	v_max_f32_e32 v65, v236, v236
	v_max_f32_e32 v64, v65, v64
	v_max3_f32 v64, v64, v238, v239
	v_max3_f32 v64, v64, v240, v241
	v_max3_f32 v64, v64, v242, v243
	v_max3_f32 v64, v64, v244, v245
	v_max3_f32 v64, v64, v246, v247
	v_max3_f32 v64, v64, v248, v249
	v_max3_f32 v64, v64, v250, v251
	v_mov_b32_e32 v65, v64
	s_nop 1
	v_permlane32_swap_b32_e32 v64, v65
	v_max_f32_e32 v65, v65, v65
	v_max_f32_e32 v64, v64, v64
	v_max_f32_e32 v64, v64, v65
	v_cmp_lt_f32_e32 vcc, s97, v64
	s_cbranch_vccnz .Ldf_rare1_0
	s_waitcnt lgkmcnt(3)
	v_mfma_f32_32x32x16_bf16 v[32:47], v[200:203], v[130:133], v[32:47]
	ds_read_b128 v[126:129], v195 offset:16384
	ds_read_b128 v[114:117], v195 offset:20480
	v_exp_f32_e32 v236, v236
	v_exp_f32_e32 v237, v237
	v_exp_f32_e32 v238, v238
	s_waitcnt lgkmcnt(4)
	v_mfma_f32_32x32x16_bf16 v[48:63], v[200:203], v[134:137], v[48:63]
	ds_read_b128 v[122:125], v196 offset:16384
	ds_read_b128 v[118:121], v196 offset:20480
	v_exp_f32_e32 v239, v239
	v_exp_f32_e32 v240, v240
	v_exp_f32_e32 v241, v241
	s_waitcnt lgkmcnt(5)
	v_mfma_f32_32x32x16_bf16 v[32:47], v[204:207], v[138:141], v[32:47]
	v_exp_f32_e32 v242, v242
	v_exp_f32_e32 v243, v243
	v_exp_f32_e32 v244, v244
	s_waitcnt lgkmcnt(4)
	v_mfma_f32_32x32x16_bf16 v[48:63], v[204:207], v[142:145], v[48:63]
	v_exp_f32_e32 v245, v245
	v_exp_f32_e32 v246, v246
	v_exp_f32_e32 v247, v247
	v_exp_f32_e32 v248, v248
	v_exp_f32_e32 v249, v249
	v_exp_f32_e32 v250, v250
	v_exp_f32_e32 v251, v251
	v_cvt_pk_bf16_f32 v160, v236, v237
	v_cvt_pk_bf16_f32 v161, v238, v239
	v_cvt_pk_bf16_f32 v162, v240, v241
	v_cvt_pk_bf16_f32 v163, v242, v243
	v_cvt_pk_bf16_f32 v164, v244, v245
	v_cvt_pk_bf16_f32 v165, v246, v247
	v_cvt_pk_bf16_f32 v166, v248, v249
	v_cvt_pk_bf16_f32 v167, v250, v251
.Ldf_join1_0:
	s_waitcnt lgkmcnt(3)
	v_mfma_f32_32x32x16_bf16 v[0:15], v[160:163], v[126:129], v[0:15]
	ds_read_b128 v[130:133], v195 offset:24576
	ds_read_b128 v[134:137], v195 offset:28672
	v_add_f32_e32 v168, v236, v237
	v_add_f32_e32 v169, v238, v239
	v_add_f32_e32 v170, v240, v241
	v_add_f32_e32 v171, v242, v243
	v_add_f32_e32 v172, v244, v245
	v_add_f32_e32 v173, v246, v247
	s_waitcnt lgkmcnt(4)
	v_mfma_f32_32x32x16_bf16 v[16:31], v[160:163], v[114:117], v[16:31]
	ds_read_b128 v[138:141], v196 offset:24576
	ds_read_b128 v[142:145], v196 offset:28672
	v_add_f32_e32 v174, v248, v249
	v_add_f32_e32 v175, v250, v251
	v_add_f32_e32 v168, v168, v169
	v_add_f32_e32 v170, v170, v171
	v_add_f32_e32 v172, v172, v173
	s_waitcnt lgkmcnt(5)
	v_mfma_f32_32x32x16_bf16 v[0:15], v[164:167], v[122:125], v[0:15]
	v_add_f32_e32 v174, v174, v175
	v_add_f32_e32 v168, v168, v170
	v_add_f32_e32 v172, v172, v174
	v_add_f32_e32 v168, v168, v172
	v_add_f32_e32 v184, v184, v168
	s_waitcnt lgkmcnt(4)
	v_mfma_f32_32x32x16_bf16 v[16:31], v[164:167], v[118:121], v[16:31]
	s_waitcnt lgkmcnt(3)
	v_mfma_f32_32x32x16_bf16 v[32:47], v[160:163], v[130:133], v[32:47]
	s_waitcnt lgkmcnt(2)
	v_mfma_f32_32x32x16_bf16 v[48:63], v[160:163], v[134:137], v[48:63]
	s_waitcnt lgkmcnt(1)
	v_mfma_f32_32x32x16_bf16 v[32:47], v[164:167], v[138:141], v[32:47]
	s_waitcnt lgkmcnt(0)
	v_mfma_f32_32x32x16_bf16 v[48:63], v[164:167], v[142:145], v[48:63]
	s_waitcnt vmcnt(3)
	ds_write_b128 v180, v[98:101] offset:32768
	s_waitcnt vmcnt(2)
	ds_write_b128 v180, v[102:105] offset:40960
	s_waitcnt vmcnt(0)
	ds_write2st64_b64 v178, v[106:107], v[110:111] offset0:96 offset1:112
	ds_write2st64_b64 v179, v[108:109], v[112:113] offset0:96 offset1:112
	s_waitcnt lgkmcnt(0)
	s_barrier
	ds_read_b128 v[114:117], v181 offset:32768
	ds_read_b128 v[118:121], v182 offset:32768
	ds_read_b128 v[122:125], v183 offset:32768
	ds_read_b128 v[126:129], v192 offset:32768
	ds_read_b128 v[142:145], v181 offset:40960
	ds_read_b128 v[138:141], v182 offset:40960
	ds_read_b128 v[134:137], v183 offset:40960
	ds_read_b128 v[130:133], v192 offset:40960
	s_cmp_ge_u32 s64, s18
	s_cselect_b64 s[16:17], -1, 0
	s_cbranch_scc1 .Ldf_nold1
	v_add_co_u32_e32 v64, vcc, 0xfffdc000, v150
	s_nop 1
	v_addc_co_u32_e32 v65, vcc, -1, v151, vcc
	global_load_dwordx4 v[98:101], v[64:65], off
	global_load_dwordx4 v[102:105], v[150:151], off
	v_add_co_u32_e32 v64, vcc, 0x2f800000, v158
	s_nop 1
	v_addc_co_u32_e32 v65, vcc, 0, v159, vcc
	global_load_dwordx4 v[106:109], v[64:65], off offset:512
	v_add_co_u32_e32 v64, vcc, 0x2f800000, v156
	s_nop 1
	v_addc_co_u32_e32 v65, vcc, 0, v157, vcc
	global_load_dwordx4 v[110:113], v[64:65], off offset:512
.Ldf_nold1:
	s_cmp_le_i32 s68, s19
	s_cselect_b64 s[54:55], -1, 0
	s_cmp_gt_i32 s68, s19
	s_cselect_b64 vcc, -1, 0
	s_sub_i32 s4, s69, 31
	s_cmpk_gt_i32 s4, 0x7f
	s_cselect_b64 s[70:71], -1, 0
	s_and_b64 s[4:5], vcc, s[70:71]
	v_cndmask_b32_e64 v64, 0, v147, s[4:5]
	v_cndmask_b32_e32 v253, v146, v64, vcc
	s_or_b64 s[4:5], s[54:55], s[70:71]
	v_sub_f32_e32 v64, v253, v149
	v_cmp_ne_u32_e32 vcc, v64, v220
	s_cbranch_vccz .Ldf_ci1
	v_mov_b32_e32 v220, v64
	v_mov_b32_e32 v221, v64
	v_mov_b32_e32 v222, v64
	v_mov_b32_e32 v223, v64
	v_mov_b32_e32 v224, v64
	v_mov_b32_e32 v225, v64
	v_mov_b32_e32 v226, v64
	v_mov_b32_e32 v227, v64
	v_mov_b32_e32 v228, v64
	v_mov_b32_e32 v229, v64
	v_mov_b32_e32 v230, v64
	v_mov_b32_e32 v231, v64
	v_mov_b32_e32 v232, v64
	v_mov_b32_e32 v233, v64
	v_mov_b32_e32 v234, v64
	v_mov_b32_e32 v235, v64
.Ldf_ci1:
	s_nop 0
	s_waitcnt lgkmcnt(7)
	v_mfma_f32_32x32x16_bf16 v[66:81], v[114:117], v[82:85], v[220:235]
	s_waitcnt lgkmcnt(6)
	v_mfma_f32_32x32x16_bf16 v[66:81], v[118:121], v[86:89], v[66:81]
	s_waitcnt lgkmcnt(5)
	v_mfma_f32_32x32x16_bf16 v[66:81], v[122:125], v[90:93], v[66:81]
	s_waitcnt lgkmcnt(4)
	v_mfma_f32_32x32x16_bf16 v[66:81], v[126:129], v[94:97], v[66:81]
	s_waitcnt lgkmcnt(3)
	v_mfma_f32_32x32x16_bf16 v[236:251], v[142:145], v[82:85], v[220:235]
	ds_read_b128 v[126:129], v193 offset:49152
	ds_read_b128 v[114:117], v193 offset:53248
	s_waitcnt lgkmcnt(4)
	v_mfma_f32_32x32x16_bf16 v[236:251], v[138:141], v[86:89], v[236:251]
	ds_read_b128 v[122:125], v194 offset:49152
	ds_read_b128 v[118:121], v194 offset:53248
	s_waitcnt lgkmcnt(5)
	v_mfma_f32_32x32x16_bf16 v[236:251], v[134:137], v[90:93], v[236:251]
	s_waitcnt lgkmcnt(4)
	v_mfma_f32_32x32x16_bf16 v[236:251], v[130:133], v[94:97], v[236:251]
	ds_read_b128 v[130:133], v193 offset:57344
	ds_read_b128 v[134:137], v193 offset:61440
	ds_read_b128 v[138:141], v194 offset:57344
	ds_read_b128 v[142:145], v194 offset:61440
	s_and_b64 vcc, exec, s[4:5]
	s_cbranch_vccnz .Ldf_nb0_1
	ds_read2_b32 v[160:161], v148 offset0:64 offset1:65
	ds_read2_b32 v[162:163], v148 offset0:66 offset1:67
	ds_read2_b32 v[164:165], v148 offset0:72 offset1:73
	ds_read2_b32 v[166:167], v148 offset0:74 offset1:75
	ds_read2_b32 v[168:169], v148 offset0:80 offset1:81
	ds_read2_b32 v[170:171], v148 offset0:82 offset1:83
	ds_read2_b32 v[172:173], v148 offset0:88 offset1:89
	ds_read2_b32 v[174:175], v148 offset0:90 offset1:91
	s_waitcnt lgkmcnt(7)
	v_pk_add_f32 v[66:67], v[66:67], v[160:161]
	s_waitcnt lgkmcnt(6)
	v_pk_add_f32 v[68:69], v[68:69], v[162:163]
	s_waitcnt lgkmcnt(5)
	v_pk_add_f32 v[70:71], v[70:71], v[164:165]
	s_waitcnt lgkmcnt(4)
	v_pk_add_f32 v[72:73], v[72:73], v[166:167]
	s_waitcnt lgkmcnt(3)
	v_pk_add_f32 v[74:75], v[74:75], v[168:169]
	s_waitcnt lgkmcnt(2)
	v_pk_add_f32 v[76:77], v[76:77], v[170:171]
	s_waitcnt lgkmcnt(1)
	v_pk_add_f32 v[78:79], v[78:79], v[172:173]
	s_waitcnt lgkmcnt(0)
	v_pk_add_f32 v[80:81], v[80:81], v[174:175]
	s_nop 0

; template <int KW, int DV, bool BIAS> ...
;     ...
;     for (int t = 0; t < NT; t += 2) { TILE(0, t); TILE(1, t + 1); }
.Ldf_back0_1:
	v_exp_f32_e32 v66, v66
	v_exp_f32_e32 v67, v67
	v_exp_f32_e32 v68, v68
	v_exp_f32_e32 v69, v69
	v_exp_f32_e32 v70, v70
	v_exp_f32_e32 v71, v71
	v_exp_f32_e32 v72, v72
	v_exp_f32_e32 v73, v73
	v_exp_f32_e32 v74, v74
	v_exp_f32_e32 v75, v75
	v_exp_f32_e32 v76, v76
	v_exp_f32_e32 v77, v77
	v_exp_f32_e32 v78, v78
	v_exp_f32_e32 v79, v79
	v_exp_f32_e32 v80, v80
	v_exp_f32_e32 v81, v81
	v_cvt_pk_bf16_f32 v200, v66, v67
	v_cvt_pk_bf16_f32 v201, v68, v69
	v_cvt_pk_bf16_f32 v202, v70, v71
	v_cvt_pk_bf16_f32 v203, v72, v73
	v_cvt_pk_bf16_f32 v204, v74, v75
	v_cvt_pk_bf16_f32 v205, v76, v77
	v_cvt_pk_bf16_f32 v206, v78, v79
	v_cvt_pk_bf16_f32 v207, v80, v81
	s_waitcnt lgkmcnt(7)
	v_mfma_f32_32x32x16_bf16 v[0:15], v[200:203], v[126:129], v[0:15]
	v_add_f32_e32 v168, v66, v67
	v_add_f32_e32 v169, v68, v69
	v_add_f32_e32 v170, v70, v71
	v_add_f32_e32 v171, v72, v73
	v_add_f32_e32 v172, v74, v75
	v_add_f32_e32 v173, v76, v77
	s_waitcnt lgkmcnt(6)
	v_mfma_f32_32x32x16_bf16 v[16:31], v[200:203], v[114:117], v[16:31]
	v_add_f32_e32 v174, v78, v79
	v_add_f32_e32 v175, v80, v81
	v_add_f32_e32 v168, v168, v169
	v_add_f32_e32 v170, v170, v171
	v_add_f32_e32 v172, v172, v173
	s_waitcnt lgkmcnt(5)
	v_mfma_f32_32x32x16_bf16 v[0:15], v[204:207], v[122:125], v[0:15]
	v_add_f32_e32 v174, v174, v175
	v_add_f32_e32 v168, v168, v170
	v_add_f32_e32 v172, v172, v174
	v_add_f32_e32 v168, v168, v172
	v_add_f32_e32 v184, v184, v168
	s_waitcnt lgkmcnt(4)
	v_mfma_f32_32x32x16_bf16 v[16:31], v[204:207], v[118:121], v[16:31]
	s_xor_b64 s[4:5], s[4:5], -1
	s_andn2_b64 vcc, exec, s[4:5]
	s_cbranch_vccnz .Ldf_nb1_1
	ds_read2_b32 v[160:161], v148 offset0:96 offset1:97
	ds_read2_b32 v[162:163], v148 offset0:98 offset1:99
	ds_read2_b32 v[164:165], v148 offset0:104 offset1:105
	ds_read2_b32 v[166:167], v148 offset0:106 offset1:107
	ds_read2_b32 v[168:169], v148 offset0:112 offset1:113
	ds_read2_b32 v[170:171], v148 offset0:114 offset1:115
	ds_read2_b32 v[172:173], v148 offset0:120 offset1:121
	ds_read2_b32 v[174:175], v148 offset0:122 offset1:123
	s_waitcnt lgkmcnt(7)
	v_pk_add_f32 v[236:237], v[236:237], v[160:161]
	s_waitcnt lgkmcnt(6)
	v_pk_add_f32 v[238:239], v[238:239], v[162:163]
	s_waitcnt lgkmcnt(5)
	v_pk_add_f32 v[240:241], v[240:241], v[164:165]
	s_waitcnt lgkmcnt(4)
	v_pk_add_f32 v[242:243], v[242:243], v[166:167]
	s_waitcnt lgkmcnt(3)
	v_pk_add_f32 v[244:245], v[244:245], v[168:169]
	s_waitcnt lgkmcnt(2)
	v_pk_add_f32 v[246:247], v[246:247], v[170:171]
	s_waitcnt lgkmcnt(1)
	v_pk_add_f32 v[248:249], v[248:249], v[172:173]
	s_waitcnt lgkmcnt(0)
	v_pk_add_f32 v[250:251], v[250:251], v[174:175]
	s_nop 0
.Ldf_nb1_1:
	v_max_f32_e32 v64, v237, v237
	v_max_f32_e32 v65, v236, v236
	v_max_f32_e32 v64, v65, v64
	v_max3_f32 v64, v64, v238, v239
	v_max3_f32 v64, v64, v240, v241
	v_max3_f32 v64, v64, v242, v243
	v_max3_f32 v64, v64, v244, v245
	v_max3_f32 v64, v64, v246, v247
	v_max3_f32 v64, v64, v248, v249
	v_max3_f32 v64, v64, v250, v251
	v_mov_b32_e32 v65, v64
	s_nop 1
	v_permlane32_swap_b32_e32 v64, v65
	v_max_f32_e32 v65, v65, v65
	v_max_f32_e32 v64, v64, v64
	v_max_f32_e32 v64, v64, v65
	v_cmp_lt_f32_e32 vcc, s97, v64
	s_cbranch_vccnz .Ldf_rare1_1
	s_waitcnt lgkmcnt(3)
	v_mfma_f32_32x32x16_bf16 v[32:47], v[200:203], v[130:133], v[32:47]
	ds_read_b128 v[126:129], v195 offset:49152
	ds_read_b128 v[114:117], v195 offset:53248
	v_exp_f32_e32 v236, v236
	v_exp_f32_e32 v237, v237
	v_exp_f32_e32 v238, v238
	s_waitcnt lgkmcnt(4)
	v_mfma_f32_32x32x16_bf16 v[48:63], v[200:203], v[134:137], v[48:63]
	ds_read_b128 v[122:125], v196 offset:49152
	ds_read_b128 v[118:121], v196 offset:53248
	v_exp_f32_e32 v239, v239
	v_exp_f32_e32 v240, v240
	v_exp_f32_e32 v241, v241
	s_waitcnt lgkmcnt(5)
	v_mfma_f32_32x32x16_bf16 v[32:47], v[204:207], v[138:141], v[32:47]
	v_exp_f32_e32 v242, v242
	v_exp_f32_e32 v243, v243
	v_exp_f32_e32 v244, v244
	s_waitcnt lgkmcnt(4)
	v_mfma_f32_32x32x16_bf16 v[48:63], v[204:207], v[142:145], v[48:63]
	v_exp_f32_e32 v245, v245
	v_exp_f32_e32 v246, v246
	v_exp_f32_e32 v247, v247
	v_exp_f32_e32 v248, v248
	v_exp_f32_e32 v249, v249
	v_exp_f32_e32 v250, v250
	v_exp_f32_e32 v251, v251
	v_cvt_pk_bf16_f32 v160, v236, v237
	v_cvt_pk_bf16_f32 v161, v238, v239
	v_cvt_pk_bf16_f32 v162, v240, v241
	v_cvt_pk_bf16_f32 v163, v242, v243
	v_cvt_pk_bf16_f32 v164, v244, v245
	v_cvt_pk_bf16_f32 v165, v246, v247
	v_cvt_pk_bf16_f32 v166, v248, v249
	v_cvt_pk_bf16_f32 v167, v250, v251
.Ldf_join1_1:
	s_waitcnt lgkmcnt(3)
	v_mfma_f32_32x32x16_bf16 v[0:15], v[160:163], v[126:129], v[0:15]
	ds_read_b128 v[130:133], v195 offset:57344
	ds_read_b128 v[134:137], v195 offset:61440
	v_add_f32_e32 v168, v236, v237
	v_add_f32_e32 v169, v238, v239
	v_add_f32_e32 v170, v240, v241
	v_add_f32_e32 v171, v242, v243
	v_add_f32_e32 v172, v244, v245
	v_add_f32_e32 v173, v246, v247
	s_waitcnt lgkmcnt(4)
	v_mfma_f32_32x32x16_bf16 v[16:31], v[160:163], v[114:117], v[16:31]
	ds_read_b128 v[138:141], v196 offset:57344
	ds_read_b128 v[142:145], v196 offset:61440
	v_add_f32_e32 v174, v248, v249
	v_add_f32_e32 v175, v250, v251
	v_add_f32_e32 v168, v168, v169
	v_add_f32_e32 v170, v170, v171
	v_add_f32_e32 v172, v172, v173
	s_waitcnt lgkmcnt(5)
	v_mfma_f32_32x32x16_bf16 v[0:15], v[164:167], v[122:125], v[0:15]
	v_add_f32_e32 v174, v174, v175
	v_add_f32_e32 v168, v168, v170
	v_add_f32_e32 v172, v172, v174
	v_add_f32_e32 v168, v168, v172
	v_add_f32_e32 v184, v184, v168
	s_waitcnt lgkmcnt(4)
	v_mfma_f32_32x32x16_bf16 v[16:31], v[164:167], v[118:121], v[16:31]
	s_waitcnt lgkmcnt(3)
	v_mfma_f32_32x32x16_bf16 v[32:47], v[160:163], v[130:133], v[32:47]
	s_waitcnt lgkmcnt(2)
	v_mfma_f32_32x32x16_bf16 v[48:63], v[160:163], v[134:137], v[48:63]
	s_waitcnt lgkmcnt(1)
	v_mfma_f32_32x32x16_bf16 v[32:47], v[164:167], v[138:141], v[32:47]
	s_waitcnt lgkmcnt(0)
	v_mfma_f32_32x32x16_bf16 v[48:63], v[164:167], v[142:145], v[48:63]
	v_lshl_add_u64 v[150:151], v[150:151], 0, s[94:95]
	v_lshl_add_u64 v[152:153], v[152:153], 0, s[84:85]
	v_lshl_add_u64 v[154:155], v[154:155], 0, s[84:85]
	s_add_i32 s64, s64, 2
	v_add_u32_e32 v148, 0x200, v148
	s_andn2_b64 vcc, exec, s[16:17]
	s_addk_i32 s68, 0x80
	s_cbranch_vccnz .LBB0_268
	s_branch .Ldf_exit
.Ldf_rare0_0:
	s_nop 15
	v_max_f32_e32 v65, v64, v64
	v_max_f32_e32 v65, 0, v65
	v_add_f32_e32 v149, v149, v65
	v_sub_f32_e32 v66, v66, v65
	v_sub_f32_e32 v67, v67, v65
	v_sub_f32_e32 v68, v68, v65
	v_sub_f32_e32 v69, v69, v65
	v_sub_f32_e32 v70, v70, v65
	v_sub_f32_e32 v71, v71, v65
	v_sub_f32_e32 v72, v72, v65
	v_sub_f32_e32 v73, v73, v65
	v_sub_f32_e32 v74, v74, v65
	v_sub_f32_e32 v75, v75, v65
	v_sub_f32_e32 v76, v76, v65
	v_sub_f32_e32 v77, v77, v65
	v_sub_f32_e32 v78, v78, v65
	v_sub_f32_e32 v79, v79, v65
	v_sub_f32_e32 v80, v80, v65
	v_sub_f32_e32 v81, v81, v65
	v_sub_f32_e32 v236, v236, v65
	v_sub_f32_e32 v237, v237, v65
	v_sub_f32_e32 v238, v238, v65
	v_sub_f32_e32 v239, v239, v65
	v_sub_f32_e32 v240, v240, v65
	v_sub_f32_e32 v241, v241, v65
	v_sub_f32_e32 v242, v242, v65
	v_sub_f32_e32 v243, v243, v65
	v_sub_f32_e32 v244, v244, v65
	v_sub_f32_e32 v245, v245, v65
	v_sub_f32_e32 v246, v246, v65
	v_sub_f32_e32 v247, v247, v65
	v_sub_f32_e32 v248, v248, v65
	v_sub_f32_e32 v249, v249, v65
	v_sub_f32_e32 v250, v250, v65
	v_sub_f32_e32 v251, v251, v65
	v_exp_f32_e64 v64, -v65
	s_nop 0
	ds_write_b32 v198, v64
	ds_read_b128 v[160:163], v197
	ds_read_b128 v[164:167], v197 offset:32
	ds_read_b128 v[168:171], v197 offset:64
	ds_read_b128 v[172:175], v197 offset:96
	v_mul_f32_e32 v184, v184, v64
	s_waitcnt lgkmcnt(0)
	v_pk_mul_f32 v[0:1], v[0:1], v[160:161]
	v_pk_mul_f32 v[2:3], v[2:3], v[162:163]
	v_pk_mul_f32 v[4:5], v[4:5], v[164:165]
	v_pk_mul_f32 v[6:7], v[6:7], v[166:167]
	v_pk_mul_f32 v[8:9], v[8:9], v[168:169]
	v_pk_mul_f32 v[10:11], v[10:11], v[170:171]
	v_pk_mul_f32 v[12:13], v[12:13], v[172:173]
	v_pk_mul_f32 v[14:15], v[14:15], v[174:175]
	v_pk_mul_f32 v[16:17], v[16:17], v[160:161]
	v_pk_mul_f32 v[18:19], v[18:19], v[162:163]
	v_pk_mul_f32 v[20:21], v[20:21], v[164:165]
	v_pk_mul_f32 v[22:23], v[22:23], v[166:167]
	v_pk_mul_f32 v[24:25], v[24:25], v[168:169]
	v_pk_mul_f32 v[26:27], v[26:27], v[170:171]
	v_pk_mul_f32 v[28:29], v[28:29], v[172:173]
	v_pk_mul_f32 v[30:31], v[30:31], v[174:175]
	v_pk_mul_f32 v[32:33], v[32:33], v[160:161]
	v_pk_mul_f32 v[34:35], v[34:35], v[162:163]
	v_pk_mul_f32 v[36:37], v[36:37], v[164:165]
	v_pk_mul_f32 v[38:39], v[38:39], v[166:167]
	v_pk_mul_f32 v[40:41], v[40:41], v[168:169]
	v_pk_mul_f32 v[42:43], v[42:43], v[170:171]
	v_pk_mul_f32 v[44:45], v[44:45], v[172:173]
	v_pk_mul_f32 v[46:47], v[46:47], v[174:175]
	v_pk_mul_f32 v[48:49], v[48:49], v[160:161]
	v_pk_mul_f32 v[50:51], v[50:51], v[162:163]
	v_pk_mul_f32 v[52:53], v[52:53], v[164:165]
	v_pk_mul_f32 v[54:55], v[54:55], v[166:167]
	v_pk_mul_f32 v[56:57], v[56:57], v[168:169]
	v_pk_mul_f32 v[58:59], v[58:59], v[170:171]
	v_pk_mul_f32 v[60:61], v[60:61], v[172:173]
	v_pk_mul_f32 v[62:63], v[62:63], v[174:175]
	v_sub_f32_e32 v64, v253, v149
	v_mov_b32_e32 v220, v64
	v_mov_b32_e32 v221, v64
	v_mov_b32_e32 v222, v64
	v_mov_b32_e32 v223, v64
	v_mov_b32_e32 v224, v64
	v_mov_b32_e32 v225, v64
	v_mov_b32_e32 v226, v64
	v_mov_b32_e32 v227, v64
	v_mov_b32_e32 v228, v64
	v_mov_b32_e32 v229, v64
	v_mov_b32_e32 v230, v64
	v_mov_b32_e32 v231, v64
	v_mov_b32_e32 v232, v64
	v_mov_b32_e32 v233, v64
	v_mov_b32_e32 v234, v64
	v_mov_b32_e32 v235, v64
	s_branch .Ldf_back0_0
.Ldf_rare1_0:
	s_waitcnt lgkmcnt(0)
	v_mfma_f32_32x32x16_bf16 v[32:47], v[200:203], v[130:133], v[32:47]
	v_mfma_f32_32x32x16_bf16 v[48:63], v[200:203], v[134:137], v[48:63]
	v_mfma_f32_32x32x16_bf16 v[32:47], v[204:207], v[138:141], v[32:47]
	v_mfma_f32_32x32x16_bf16 v[48:63], v[204:207], v[142:145], v[48:63]
	s_nop 15
	v_max_f32_e32 v65, v64, v64
	v_max_f32_e32 v65, 0, v65
	v_add_f32_e32 v149, v149, v65
	v_sub_f32_e32 v236, v236, v65
	v_sub_f32_e32 v237, v237, v65
	v_sub_f32_e32 v238, v238, v65
	v_sub_f32_e32 v239, v239, v65
	v_sub_f32_e32 v240, v240, v65
	v_sub_f32_e32 v241, v241, v65
	v_sub_f32_e32 v242, v242, v65
	v_sub_f32_e32 v243, v243, v65
	v_sub_f32_e32 v244, v244, v65
	v_sub_f32_e32 v245, v245, v65
	v_sub_f32_e32 v246, v246, v65
	v_sub_f32_e32 v247, v247, v65
	v_sub_f32_e32 v248, v248, v65
	v_sub_f32_e32 v249, v249, v65
	v_sub_f32_e32 v250, v250, v65
	v_sub_f32_e32 v251, v251, v65
	v_exp_f32_e64 v64, -v65
	s_nop 0
	ds_write_b32 v198, v64
	ds_read_b128 v[160:163], v197
	ds_read_b128 v[164:167], v197 offset:32
	ds_read_b128 v[168:171], v197 offset:64
	ds_read_b128 v[172:175], v197 offset:96
	v_mul_f32_e32 v184, v184, v64
	s_waitcnt lgkmcnt(0)
	v_pk_mul_f32 v[0:1], v[0:1], v[160:161]
	v_pk_mul_f32 v[2:3], v[2:3], v[162:163]
	v_pk_mul_f32 v[4:5], v[4:5], v[164:165]
	v_pk_mul_f32 v[6:7], v[6:7], v[166:167]
	v_pk_mul_f32 v[8:9], v[8:9], v[168:169]
	v_pk_mul_f32 v[10:11], v[10:11], v[170:171]
	v_pk_mul_f32 v[12:13], v[12:13], v[172:173]
	v_pk_mul_f32 v[14:15], v[14:15], v[174:175]
	v_pk_mul_f32 v[16:17], v[16:17], v[160:161]
	v_pk_mul_f32 v[18:19], v[18:19], v[162:163]
	v_pk_mul_f32 v[20:21], v[20:21], v[164:165]
	v_pk_mul_f32 v[22:23], v[22:23], v[166:167]
	v_pk_mul_f32 v[24:25], v[24:25], v[168:169]
	v_pk_mul_f32 v[26:27], v[26:27], v[170:171]
	v_pk_mul_f32 v[28:29], v[28:29], v[172:173]
	v_pk_mul_f32 v[30:31], v[30:31], v[174:175]
	v_pk_mul_f32 v[32:33], v[32:33], v[160:161]
	v_pk_mul_f32 v[34:35], v[34:35], v[162:163]
	v_pk_mul_f32 v[36:37], v[36:37], v[164:165]
	v_pk_mul_f32 v[38:39], v[38:39], v[166:167]
	v_pk_mul_f32 v[40:41], v[40:41], v[168:169]
	v_pk_mul_f32 v[42:43], v[42:43], v[170:171]
	v_pk_mul_f32 v[44:45], v[44:45], v[172:173]
	v_pk_mul_f32 v[46:47], v[46:47], v[174:175]
	v_pk_mul_f32 v[48:49], v[48:49], v[160:161]
	v_pk_mul_f32 v[50:51], v[50:51], v[162:163]
	v_pk_mul_f32 v[52:53], v[52:53], v[164:165]
	v_pk_mul_f32 v[54:55], v[54:55], v[166:167]
	v_pk_mul_f32 v[56:57], v[56:57], v[168:169]
	v_pk_mul_f32 v[58:59], v[58:59], v[170:171]
	v_pk_mul_f32 v[60:61], v[60:61], v[172:173]
	v_pk_mul_f32 v[62:63], v[62:63], v[174:175]
	ds_read_b128 v[126:129], v195 offset:16384
	ds_read_b128 v[114:117], v195 offset:20480
	ds_read_b128 v[122:125], v196 offset:16384
	ds_read_b128 v[118:121], v196 offset:20480
	v_exp_f32_e32 v236, v236
	v_exp_f32_e32 v237, v237
	v_exp_f32_e32 v238, v238
	v_exp_f32_e32 v239, v239
	v_exp_f32_e32 v240, v240
	v_exp_f32_e32 v241, v241
	v_exp_f32_e32 v242, v242
	v_exp_f32_e32 v243, v243
	v_exp_f32_e32 v244, v244
	v_exp_f32_e32 v245, v245
	v_exp_f32_e32 v246, v246
	v_exp_f32_e32 v247, v247
	v_exp_f32_e32 v248, v248
	v_exp_f32_e32 v249, v249
	v_exp_f32_e32 v250, v250
	v_exp_f32_e32 v251, v251
	v_cvt_pk_bf16_f32 v160, v236, v237
	v_cvt_pk_bf16_f32 v161, v238, v239
	v_cvt_pk_bf16_f32 v162, v240, v241
	v_cvt_pk_bf16_f32 v163, v242, v243
	v_cvt_pk_bf16_f32 v164, v244, v245
	v_cvt_pk_bf16_f32 v165, v246, v247
	v_cvt_pk_bf16_f32 v166, v248, v249
	v_cvt_pk_bf16_f32 v167, v250, v251
	s_branch .Ldf_join1_0

; __device__ __forceinline__ float xsum32(float v) { auto rr = __builtin_amdgcn_permlane32_swap(__float_as_uint(v), __float_as_uint(v), false, false); return __uint_as_float(rr[0]) + __uint_as_float(rr[1]); }
; template <int KW, int DV, bool BIAS> ...
;     ...
;     l = xsum32(l);
;     wsf[r32] = 1.f / l;
.Ldf_rare1_1:
	s_waitcnt lgkmcnt(0)
	v_mfma_f32_32x32x16_bf16 v[32:47], v[200:203], v[130:133], v[32:47]
	v_mfma_f32_32x32x16_bf16 v[48:63], v[200:203], v[134:137], v[48:63]
	v_mfma_f32_32x32x16_bf16 v[32:47], v[204:207], v[138:141], v[32:47]
	v_mfma_f32_32x32x16_bf16 v[48:63], v[204:207], v[142:145], v[48:63]
	s_nop 15
	v_max_f32_e32 v65, v64, v64
	v_max_f32_e32 v65, 0, v65
	v_add_f32_e32 v149, v149, v65
	v_sub_f32_e32 v236, v236, v65
	v_sub_f32_e32 v237, v237, v65
	v_sub_f32_e32 v238, v238, v65
	v_sub_f32_e32 v239, v239, v65
	v_sub_f32_e32 v240, v240, v65
	v_sub_f32_e32 v241, v241, v65
	v_sub_f32_e32 v242, v242, v65
	v_sub_f32_e32 v243, v243, v65
	v_sub_f32_e32 v244, v244, v65
	v_sub_f32_e32 v245, v245, v65
	v_sub_f32_e32 v246, v246, v65
	v_sub_f32_e32 v247, v247, v65
	v_sub_f32_e32 v248, v248, v65
	v_sub_f32_e32 v249, v249, v65
	v_sub_f32_e32 v250, v250, v65
	v_sub_f32_e32 v251, v251, v65
	v_exp_f32_e64 v64, -v65
	s_nop 0
	ds_write_b32 v198, v64
	ds_read_b128 v[160:163], v197
	ds_read_b128 v[164:167], v197 offset:32
	ds_read_b128 v[168:171], v197 offset:64
	ds_read_b128 v[172:175], v197 offset:96
	v_mul_f32_e32 v184, v184, v64
	s_waitcnt lgkmcnt(0)
	v_pk_mul_f32 v[0:1], v[0:1], v[160:161]
	v_pk_mul_f32 v[2:3], v[2:3], v[162:163]
	v_pk_mul_f32 v[4:5], v[4:5], v[164:165]
	v_pk_mul_f32 v[6:7], v[6:7], v[166:167]
	v_pk_mul_f32 v[8:9], v[8:9], v[168:169]
	v_pk_mul_f32 v[10:11], v[10:11], v[170:171]
	v_pk_mul_f32 v[12:13], v[12:13], v[172:173]
	v_pk_mul_f32 v[14:15], v[14:15], v[174:175]
	v_pk_mul_f32 v[16:17], v[16:17], v[160:161]
	v_pk_mul_f32 v[18:19], v[18:19], v[162:163]
	v_pk_mul_f32 v[20:21], v[20:21], v[164:165]
	v_pk_mul_f32 v[22:23], v[22:23], v[166:167]
	v_pk_mul_f32 v[24:25], v[24:25], v[168:169]
	v_pk_mul_f32 v[26:27], v[26:27], v[170:171]
	v_pk_mul_f32 v[28:29], v[28:29], v[172:173]
	v_pk_mul_f32 v[30:31], v[30:31], v[174:175]
	v_pk_mul_f32 v[32:33], v[32:33], v[160:161]
	v_pk_mul_f32 v[34:35], v[34:35], v[162:163]
	v_pk_mul_f32 v[36:37], v[36:37], v[164:165]
	v_pk_mul_f32 v[38:39], v[38:39], v[166:167]
	v_pk_mul_f32 v[40:41], v[40:41], v[168:169]
	v_pk_mul_f32 v[42:43], v[42:43], v[170:171]
	v_pk_mul_f32 v[44:45], v[44:45], v[172:173]
	v_pk_mul_f32 v[46:47], v[46:47], v[174:175]
	v_pk_mul_f32 v[48:49], v[48:49], v[160:161]
	v_pk_mul_f32 v[50:51], v[50:51], v[162:163]
	v_pk_mul_f32 v[52:53], v[52:53], v[164:165]
	v_pk_mul_f32 v[54:55], v[54:55], v[166:167]
	v_pk_mul_f32 v[56:57], v[56:57], v[168:169]
	v_pk_mul_f32 v[58:59], v[58:59], v[170:171]
	v_pk_mul_f32 v[60:61], v[60:61], v[172:173]
	v_pk_mul_f32 v[62:63], v[62:63], v[174:175]
	ds_read_b128 v[126:129], v195 offset:49152
	ds_read_b128 v[114:117], v195 offset:53248
	ds_read_b128 v[122:125], v196 offset:49152
	ds_read_b128 v[118:121], v196 offset:53248
	v_exp_f32_e32 v236, v236
	v_exp_f32_e32 v237, v237
	v_exp_f32_e32 v238, v238
	v_exp_f32_e32 v239, v239
	v_exp_f32_e32 v240, v240
	v_exp_f32_e32 v241, v241
	v_exp_f32_e32 v242, v242
	v_exp_f32_e32 v243, v243
	v_exp_f32_e32 v244, v244
	v_exp_f32_e32 v245, v245
	v_exp_f32_e32 v246, v246
	v_exp_f32_e32 v247, v247
	v_exp_f32_e32 v248, v248
	v_exp_f32_e32 v249, v249
	v_exp_f32_e32 v250, v250
	v_exp_f32_e32 v251, v251
	v_cvt_pk_bf16_f32 v160, v236, v237
	v_cvt_pk_bf16_f32 v161, v238, v239
	v_cvt_pk_bf16_f32 v162, v240, v241
	v_cvt_pk_bf16_f32 v163, v242, v243
	v_cvt_pk_bf16_f32 v164, v244, v245
	v_cvt_pk_bf16_f32 v165, v246, v247
	v_cvt_pk_bf16_f32 v166, v248, v249
	v_cvt_pk_bf16_f32 v167, v250, v251
	s_branch .Ldf_join1_1
.Ldf_exit:
	v_mov_b32_e32 v174, v184
